# LN1 router mat-vec rewritten by hand on packed f32 FMAs (different f32 summation order), LDS weight reads double-buffered
# speedup vs baseline: 1.0085x; 1.0035x over previous
; #define LAS __attribute__((address_space(3)))
; __device__ __forceinline__ float bf2f(unsigned b) { return __uint_as_float(b << 16); }
; __device__ __forceinline__ void ln_stats(const f32x4 (&v)[4], float& mean, float& rstd) {
;     float s = 0.f;
; #pragma unroll
;     for (int j = 0; j < 4; ++j) s += (v[j][0] + v[j][1]) + (v[j][2] + v[j][3]);
;     mean = wave_sum(s) * (1.f / 1024.f); float q = 0.f;
; #pragma unroll
;     for (int j = 0; j < 4; ++j) { const f32x4 d = v[j] - mean; q += (d[0] * d[0] + d[1] * d[1]) + (d[2] * d[2] + d[3] * d[3]); }
;     rstd = 1.0f / sqrtf(wave_sum(q) * (1.f / 1024.f) + LN_EPS);
; }
; __device__ __forceinline__ void phase_ln1(const Args& a, LAS unsigned char* lds, const WCtx& w, int l, int nrows) {
;     ...
;         const LAS float* bv = BV + ((row_batch(row) != b_lo) ? 3 * 1024 : 0);
;         f32x4 hv[4];
; #pragma unroll
;         for (int j = 0; j < 4; ++j) { const f32x4 g1 = *(const LAS f32x4*)(bv + 4 * w.lane + 256 * j);
;             const f32x4 yv = (f32x4){bf2f(yb[j].x & 0xffffu), bf2f(yb[j].x >> 16), bf2f(yb[j].y & 0xffffu), bf2f(yb[j].y >> 16)};
;             x[j] = x[j] * ALPHA + g1 * yv; }
;         float mean, rstd; ln_stats(x, mean, rstd);
; #pragma unroll
;         for (int j = 0; j < 4; ++j) x[j] = (x[j] - mean) * rstd * *(const LAS f32x4*)(LNG + 4 * w.lane + 256 * j) + *(const LAS f32x4*)(LNB + 4 * w.lane + 256 * j);
.LBB0_2166:
	s_min_i32 s2, s2, 0x8000
	s_ashr_i32 s2, s2, 11
	s_cmp_eq_u32 s2, s15
	s_cselect_b32 s2, 0, 0x3000
	v_add_u32_e32 v243, s2, v242
	ds_read_b128 v[244:247], v243
	s_waitcnt vmcnt(3)
	v_lshlrev_b32_e32 v226, 16, v224
	v_and_b32_e32 v227, 0xffff0000, v224
	v_lshlrev_b32_e32 v224, 16, v225
	v_and_b32_e32 v225, 0xffff0000, v225
	s_waitcnt lgkmcnt(0)
	v_pk_mul_f32 v[224:225], v[246:247], v[224:225]
	v_pk_mul_f32 v[226:227], v[244:245], v[226:227]
	s_mov_b32 s2, 0x3fd744fd
	v_pk_fma_f32 v[224:225], v[194:195], s[2:3], v[224:225] op_sel_hi:[1,0,1]
	v_pk_fma_f32 v[226:227], v[192:193], s[2:3], v[226:227] op_sel_hi:[1,0,1]
	ds_read_b128 v[192:195], v243 offset:1024
	s_waitcnt vmcnt(2)
	v_lshlrev_b32_e32 v238, 16, v222
	v_and_b32_e32 v239, 0xffff0000, v222
	v_lshlrev_b32_e32 v222, 16, v223
	v_and_b32_e32 v223, 0xffff0000, v223
	s_waitcnt lgkmcnt(0)
	v_pk_mul_f32 v[194:195], v[194:195], v[222:223]
	v_pk_mul_f32 v[192:193], v[192:193], v[238:239]
	v_pk_fma_f32 v[222:223], v[190:191], s[2:3], v[194:195] op_sel_hi:[1,0,1]
	v_pk_fma_f32 v[238:239], v[188:189], s[2:3], v[192:193] op_sel_hi:[1,0,1]
	ds_read_b128 v[188:191], v243 offset:2048
	s_waitcnt vmcnt(1)
	v_lshlrev_b32_e32 v192, 16, v220
	v_and_b32_e32 v193, 0xffff0000, v220
	v_lshlrev_b32_e32 v194, 16, v221
	v_and_b32_e32 v195, 0xffff0000, v221
	s_waitcnt lgkmcnt(0)
	v_pk_mul_f32 v[190:191], v[190:191], v[194:195]
	v_pk_mul_f32 v[188:189], v[188:189], v[192:193]
	v_pk_fma_f32 v[186:187], v[186:187], s[2:3], v[190:191] op_sel_hi:[1,0,1]
	v_pk_fma_f32 v[184:185], v[184:185], s[2:3], v[188:189] op_sel_hi:[1,0,1]
	ds_read_b128 v[188:191], v243 offset:3072
	s_waitcnt vmcnt(0)
	v_lshlrev_b32_e32 v192, 16, v218
	v_and_b32_e32 v193, 0xffff0000, v218
	v_add_f32_e32 v50, v226, v227
	v_lshlrev_b32_e32 v194, 16, v219
	s_waitcnt lgkmcnt(0)
	v_pk_mul_f32 v[188:189], v[188:189], v[192:193]
	v_and_b32_e32 v195, 0xffff0000, v219
	v_pk_fma_f32 v[220:221], v[180:181], s[2:3], v[188:189] op_sel_hi:[1,0,1]
	v_add_f32_e32 v180, v224, v225
	v_add_f32_e32 v50, v50, v180
	v_add_f32_e32 v180, v238, v239
	v_add_f32_e32 v181, v222, v223
	v_add_f32_e32 v50, 0, v50
	v_add_f32_e32 v180, v180, v181
	v_pk_mul_f32 v[190:191], v[190:191], v[194:195]
	v_add_f32_e32 v50, v180, v50
	v_add_f32_e32 v180, v184, v185
	v_add_f32_e32 v181, v186, v187
	v_pk_fma_f32 v[218:219], v[182:183], s[2:3], v[190:191] op_sel_hi:[1,0,1]
	v_add_f32_e32 v180, v180, v181
	v_add_f32_e32 v50, v180, v50
	v_add_f32_e32 v180, v220, v221
	v_add_f32_e32 v181, v218, v219
	v_add_f32_e32 v180, v180, v181
	v_add_f32_e32 v50, v180, v50
	s_mov_b32 s9, 0xf800000
	s_nop 0
	v_add_f32_dpp v50, v50, v50 quad_perm:[1,0,3,2] row_mask:0xf bank_mask:0xf bound_ctrl:1
	s_nop 1
	v_add_f32_dpp v50, v50, v50 quad_perm:[2,3,0,1] row_mask:0xf bank_mask:0xf bound_ctrl:1
	s_nop 1
	v_add_f32_dpp v50, v50, v50 row_half_mirror row_mask:0xf bank_mask:0xf bound_ctrl:1
	s_nop 1
	v_add_f32_dpp v50, v50, v50 row_mirror row_mask:0xf bank_mask:0xf bound_ctrl:1
	v_mov_b32_e32 v180, v50
	s_nop 1
	v_permlane16_swap_b32_e32 v50, v180
	v_add_f32_e32 v50, v50, v180
	v_mov_b32_e32 v180, v50
	s_nop 1
	v_permlane32_swap_b32_e32 v50, v180
	v_add_f32_e32 v50, v50, v180
	v_fmac_f32_e32 v225, 0xba800000, v50
	v_fmac_f32_e32 v227, 0xba800000, v50
	v_fmamk_f32 v224, v50, 0xba800000, v224
	v_fmamk_f32 v226, v50, 0xba800000, v226
	v_mul_f32_e32 v180, v227, v227
	v_mul_f32_e32 v181, v225, v225
	v_fmac_f32_e32 v180, v226, v226
	v_fmac_f32_e32 v181, v224, v224
	v_fmac_f32_e32 v223, 0xba800000, v50
	v_fmac_f32_e32 v239, 0xba800000, v50
	v_add_f32_e32 v180, v180, v181
	v_fmamk_f32 v222, v50, 0xba800000, v222
	v_fmamk_f32 v238, v50, 0xba800000, v238
	v_mul_f32_e32 v181, v239, v239
	v_mul_f32_e32 v182, v223, v223
	v_fmac_f32_e32 v181, v238, v238
	v_fmac_f32_e32 v182, v222, v222
	v_add_f32_e32 v181, v181, v182
	v_fmac_f32_e32 v187, 0xba800000, v50
	v_fmac_f32_e32 v185, 0xba800000, v50
	v_add_f32_e32 v180, v180, v181
	v_fmamk_f32 v186, v50, 0xba800000, v186
	v_fmamk_f32 v184, v50, 0xba800000, v184
	v_mul_f32_e32 v181, v185, v185
	v_mul_f32_e32 v182, v187, v187
	v_fmac_f32_e32 v181, v184, v184
	v_fmac_f32_e32 v182, v186, v186
	v_add_f32_e32 v181, v181, v182
	v_fmac_f32_e32 v219, 0xba800000, v50
	v_fmac_f32_e32 v221, 0xba800000, v50
	v_add_f32_e32 v180, v181, v180
	v_fmamk_f32 v218, v50, 0xba800000, v218
	v_fmamk_f32 v220, v50, 0xba800000, v220
	v_mul_f32_e32 v50, v221, v221
	v_mul_f32_e32 v181, v219, v219
	v_fmac_f32_e32 v50, v220, v220
	v_fmac_f32_e32 v181, v218, v218
	v_add_f32_e32 v50, v50, v181
	v_add_f32_e32 v50, v50, v180
	s_nop 1
	v_add_f32_dpp v50, v50, v50 quad_perm:[1,0,3,2] row_mask:0xf bank_mask:0xf bound_ctrl:1
	s_nop 1
	v_add_f32_dpp v50, v50, v50 quad_perm:[2,3,0,1] row_mask:0xf bank_mask:0xf bound_ctrl:1
	s_nop 1
	v_add_f32_dpp v50, v50, v50 row_half_mirror row_mask:0xf bank_mask:0xf bound_ctrl:1
	s_nop 1
	v_add_f32_dpp v50, v50, v50 row_mirror row_mask:0xf bank_mask:0xf bound_ctrl:1
	v_mov_b32_e32 v180, v50
	s_nop 1
	v_permlane16_swap_b32_e32 v50, v180
	v_add_f32_e32 v50, v50, v180
	v_mov_b32_e32 v180, v50
	s_nop 1
	v_permlane32_swap_b32_e32 v50, v180
	v_add_f32_e32 v50, v50, v180
	v_fmamk_f32 v50, v50, 0x3a800000, v251
	v_cmp_gt_f32_e32 vcc, s9, v50
	v_mul_f32_e32 v180, 0x4f800000, v50
	s_nop 0
	v_cndmask_b32_e32 v50, v50, v180, vcc
	v_sqrt_f32_e32 v180, v50
	s_nop 0
	v_add_u32_e32 v181, -1, v180
	v_fma_f32 v182, -v181, v180, v50
	v_cmp_ge_f32_e64 s[4:5], 0, v182
	v_add_u32_e32 v182, 1, v180
	s_nop 0
	v_cndmask_b32_e64 v181, v180, v181, s[4:5]
	v_fma_f32 v180, -v182, v180, v50
	v_cmp_lt_f32_e64 s[4:5], 0, v180
	s_nop 1
	v_cndmask_b32_e64 v180, v181, v182, s[4:5]
	v_mul_f32_e32 v181, 0x37800000, v180
	v_cndmask_b32_e32 v180, v180, v181, vcc
	v_cmp_class_f32_e32 vcc, v50, v230
	s_nop 1
	v_cndmask_b32_e32 v50, v180, v50, vcc
	v_div_scale_f32 v180, s[2:3], v50, v50, 1.0
	v_rcp_f32_e32 v181, v180
	s_mov_b32 s2, 0x9300000
	v_fma_f32 v182, -v180, v181, 1.0
	v_fmac_f32_e32 v181, v182, v181
	v_div_scale_f32 v182, vcc, 1.0, v50, 1.0
	v_mul_f32_e32 v183, v182, v181
	v_fma_f32 v188, -v180, v183, v182
	v_fmac_f32_e32 v183, v188, v181
	v_fma_f32 v180, -v180, v183, v182
	v_div_fmas_f32 v180, v180, v181, v183
	v_div_fixup_f32 v50, v180, v50, 1.0
	ds_read_b128 v[180:183], v199
	ds_read_b128 v[188:191], v241
	v_pk_mul_f32 v[194:195], v[224:225], v[50:51] op_sel_hi:[1,0]
	v_pk_mul_f32 v[192:193], v[226:227], v[50:51] op_sel_hi:[1,0]
	v_pk_mul_f32 v[222:223], v[222:223], v[50:51] op_sel_hi:[1,0]
	v_pk_mul_f32 v[224:225], v[238:239], v[50:51] op_sel_hi:[1,0]
	s_waitcnt lgkmcnt(0)
; #define LAS __attribute__((address_space(3)))
; __device__ __forceinline__ void ln_stats(const f32x4 (&v)[4], float& mean, float& rstd) {
;     float s = 0.f;
; #pragma unroll
;     for (int j = 0; j < 4; ++j) s += (v[j][0] + v[j][1]) + (v[j][2] + v[j][3]);
;     mean = wave_sum(s) * (1.f / 1024.f); float q = 0.f;
; #pragma unroll
;     for (int j = 0; j < 4; ++j) { const f32x4 d = v[j] - mean; q += (d[0] * d[0] + d[1] * d[1]) + (d[2] * d[2] + d[3] * d[3]); }
;     rstd = 1.0f / sqrtf(wave_sum(q) * (1.f / 1024.f) + LN_EPS);
; }
; __device__ __forceinline__ void phase_ln1(const Args& a, LAS unsigned char* lds, const WCtx& w, int l, int nrows) {
;     ...
;         for (int j = 0; j < 4; ++j) x[j] = (x[j] - mean) * rstd * *(const LAS f32x4*)(LNG + 4 * w.lane + 256 * j) + *(const LAS f32x4*)(LNB + 4 * w.lane + 256 * j);
;         row_store(X + (size_t)row * 1024, w.lane, x);
;         ln_stats(x, mean, rstd);
;         { unsigned* hrow = (unsigned*)((unsigned char*)H + (size_t)row * 1024);
; #pragma unroll
;           for (int j = 0; j < 4; ++j) { const f32x4 sh = *(const LAS f32x4*)(bv + 1024 + 4 * w.lane + 256 * j), sc = *(const LAS f32x4*)(bv + 2048 + 4 * w.lane + 256 * j);
;               hv[j] = (x[j] - mean) * rstd * (sc + 1.0f) + sh;
	v_pk_fma_f32 v[192:193], v[180:181], v[192:193], v[188:189]
	v_pk_fma_f32 v[194:195], v[182:183], v[194:195], v[190:191]
	ds_read_b128 v[180:183], v199 offset:1024
	ds_read_b128 v[188:191], v241 offset:1024
	v_add_co_u32_e32 v216, vcc, s2, v216
	s_waitcnt lgkmcnt(0)
	v_pk_fma_f32 v[188:189], v[180:181], v[224:225], v[188:189]
	v_pk_fma_f32 v[190:191], v[182:183], v[222:223], v[190:191]
	v_pk_mul_f32 v[222:223], v[186:187], v[50:51] op_sel_hi:[1,0]
	v_pk_mul_f32 v[224:225], v[184:185], v[50:51] op_sel_hi:[1,0]
	ds_read_b128 v[180:183], v199 offset:2048
	ds_read_b128 v[184:187], v241 offset:2048
	v_addc_co_u32_e32 v217, vcc, 0, v217, vcc
	s_waitcnt lgkmcnt(0)
	v_pk_fma_f32 v[184:185], v[180:181], v[224:225], v[184:185]
	v_pk_fma_f32 v[186:187], v[182:183], v[222:223], v[186:187]
	v_pk_mul_f32 v[222:223], v[218:219], v[50:51] op_sel_hi:[1,0]
	v_pk_mul_f32 v[224:225], v[220:221], v[50:51] op_sel_hi:[1,0]
	ds_read_b128 v[180:183], v199 offset:3072
	ds_read_b128 v[218:221], v241 offset:3072
	v_add_f32_e32 v50, v192, v193
	s_waitcnt lgkmcnt(0)
	v_pk_fma_f32 v[180:181], v[180:181], v[224:225], v[218:219]
	v_pk_fma_f32 v[182:183], v[182:183], v[222:223], v[220:221]
	global_store_dwordx4 v[216:217], v[192:195], off
	global_store_dwordx4 v[216:217], v[188:191], off offset:1024
	global_store_dwordx4 v[216:217], v[184:187], off offset:2048
	global_store_dwordx4 v[216:217], v[180:183], off offset:3072
	v_add_f32_e32 v216, v194, v195
	v_add_f32_e32 v50, v50, v216
	v_add_f32_e32 v216, v188, v189
	v_add_f32_e32 v217, v190, v191
	v_add_f32_e32 v50, 0, v50
	v_add_f32_e32 v216, v216, v217
	v_add_f32_e32 v50, v216, v50
	v_add_f32_e32 v216, v184, v185
	v_add_f32_e32 v217, v186, v187
	v_add_f32_e32 v216, v216, v217
	v_add_f32_e32 v50, v216, v50
	v_add_f32_e32 v216, v180, v181
	v_add_f32_e32 v217, v182, v183
	v_add_f32_e32 v216, v216, v217
	v_add_f32_e32 v50, v216, v50
	s_nop 1
	v_add_f32_dpp v50, v50, v50 quad_perm:[1,0,3,2] row_mask:0xf bank_mask:0xf bound_ctrl:1
	s_nop 1
	v_add_f32_dpp v50, v50, v50 quad_perm:[2,3,0,1] row_mask:0xf bank_mask:0xf bound_ctrl:1
	s_nop 1
	v_add_f32_dpp v50, v50, v50 row_half_mirror row_mask:0xf bank_mask:0xf bound_ctrl:1
	s_nop 1
	v_add_f32_dpp v50, v50, v50 row_mirror row_mask:0xf bank_mask:0xf bound_ctrl:1
	v_mov_b32_e32 v216, v50
	s_nop 1
	v_permlane16_swap_b32_e32 v50, v216
	v_add_f32_e32 v50, v50, v216
	v_mov_b32_e32 v216, v50
	s_nop 1
	v_permlane32_swap_b32_e32 v50, v216
	v_add_f32_e32 v50, v50, v216
	v_fmac_f32_e32 v195, 0xba800000, v50
	v_fmac_f32_e32 v193, 0xba800000, v50
	v_fmamk_f32 v194, v50, 0xba800000, v194
	v_fmamk_f32 v192, v50, 0xba800000, v192
	v_mul_f32_e32 v216, v193, v193
	v_mul_f32_e32 v217, v195, v195
	v_fmac_f32_e32 v216, v192, v192
	v_fmac_f32_e32 v217, v194, v194
	v_fmac_f32_e32 v191, 0xba800000, v50
	v_fmac_f32_e32 v189, 0xba800000, v50
	v_add_f32_e32 v216, v216, v217
	v_fmamk_f32 v190, v50, 0xba800000, v190
	v_fmamk_f32 v188, v50, 0xba800000, v188
	v_mul_f32_e32 v217, v189, v189
	v_mul_f32_e32 v218, v191, v191
	v_fmac_f32_e32 v217, v188, v188
	v_fmac_f32_e32 v218, v190, v190
	v_add_f32_e32 v217, v217, v218
	v_fmac_f32_e32 v187, 0xba800000, v50
	v_fmac_f32_e32 v185, 0xba800000, v50
	v_add_f32_e32 v216, v216, v217
	v_fmamk_f32 v186, v50, 0xba800000, v186
	v_fmamk_f32 v184, v50, 0xba800000, v184
	v_mul_f32_e32 v217, v185, v185
	v_mul_f32_e32 v218, v187, v187
	v_fmac_f32_e32 v217, v184, v184
	v_fmac_f32_e32 v218, v186, v186
	v_add_f32_e32 v217, v217, v218
	v_fmac_f32_e32 v183, 0xba800000, v50
	v_fmac_f32_e32 v181, 0xba800000, v50
	v_add_f32_e32 v216, v217, v216
	v_fmamk_f32 v182, v50, 0xba800000, v182
	v_fmamk_f32 v180, v50, 0xba800000, v180
	v_mul_f32_e32 v50, v181, v181
	v_mul_f32_e32 v217, v183, v183
	v_fmac_f32_e32 v50, v180, v180
	v_fmac_f32_e32 v217, v182, v182
	v_add_f32_e32 v50, v50, v217
	v_add_f32_e32 v50, v50, v216
	s_nop 1
	v_add_f32_dpp v50, v50, v50 quad_perm:[1,0,3,2] row_mask:0xf bank_mask:0xf bound_ctrl:1
	s_nop 1
	v_add_f32_dpp v50, v50, v50 quad_perm:[2,3,0,1] row_mask:0xf bank_mask:0xf bound_ctrl:1
	s_nop 1
	v_add_f32_dpp v50, v50, v50 row_half_mirror row_mask:0xf bank_mask:0xf bound_ctrl:1
	s_nop 1
	v_add_f32_dpp v50, v50, v50 row_mirror row_mask:0xf bank_mask:0xf bound_ctrl:1
	v_mov_b32_e32 v216, v50
	s_nop 1
	v_permlane16_swap_b32_e32 v50, v216
	v_add_f32_e32 v50, v50, v216
	v_mov_b32_e32 v216, v50
	s_nop 1
	v_permlane32_swap_b32_e32 v50, v216
	v_add_f32_e32 v50, v50, v216
	v_fmamk_f32 v50, v50, 0x3a800000, v251
	v_cmp_gt_f32_e32 vcc, s9, v50
	v_mul_f32_e32 v216, 0x4f800000, v50
	s_nop 0
	v_cndmask_b32_e32 v50, v50, v216, vcc
	v_sqrt_f32_e32 v216, v50
	s_nop 0
	v_add_u32_e32 v217, -1, v216
	v_fma_f32 v218, -v217, v216, v50
	v_cmp_ge_f32_e64 s[4:5], 0, v218
	v_add_u32_e32 v218, 1, v216
	s_nop 0
	v_cndmask_b32_e64 v217, v216, v217, s[4:5]
	v_fma_f32 v216, -v218, v216, v50
	v_cmp_lt_f32_e64 s[4:5], 0, v216
	s_nop 1
	v_cndmask_b32_e64 v216, v217, v218, s[4:5]
	v_mul_f32_e32 v217, 0x37800000, v216
	v_cndmask_b32_e32 v216, v216, v217, vcc
	v_cmp_class_f32_e32 vcc, v50, v230
	s_nop 1
	v_cndmask_b32_e32 v50, v216, v50, vcc
	v_div_scale_f32 v216, s[2:3], v50, v50, 1.0
	v_rcp_f32_e32 v217, v216
	s_mov_b32 s3, 0xc3e00000
	s_mov_b32 s2, 0x12300000
	v_fma_f32 v218, -v216, v217, 1.0
	v_fmac_f32_e32 v217, v218, v217
	v_div_scale_f32 v218, vcc, 1.0, v50, 1.0
	v_mul_f32_e32 v219, v218, v217
	v_fma_f32 v220, -v216, v219, v218
	v_fmac_f32_e32 v219, v220, v217
	v_fma_f32 v216, -v216, v219, v218
	v_div_fmas_f32 v216, v216, v217, v219
	v_div_fixup_f32 v50, v216, v50, 1.0
	ds_read_b128 v[216:219], v243 offset:4096
	ds_read_b128 v[220:223], v243 offset:8192
	v_pk_mul_f32 v[224:225], v[192:193], v[50:51] op_sel_hi:[1,0]
	v_pk_mul_f32 v[192:193], v[194:195], v[50:51] op_sel_hi:[1,0]
	v_pk_mul_f32 v[226:227], v[188:189], v[50:51] op_sel_hi:[1,0]
	v_pk_mul_f32 v[188:189], v[190:191], v[50:51] op_sel_hi:[1,0]
	s_waitcnt lgkmcnt(0)
; #define LAS __attribute__((address_space(3)))
; __device__ __forceinline__ float swap32_add(float a, float b) { const auto r = __builtin_amdgcn_permlane32_swap(__float_as_uint(a), __float_as_uint(b), false, false); return __uint_as_float(r[0]) + __uint_as_float(r[1]); }
; __device__ __forceinline__ unsigned pk4_fp8(float a, float b, float c, float d) { int w = 0; w = __builtin_amdgcn_cvt_pk_fp8_f32(a, b, w, false); w = __builtin_amdgcn_cvt_pk_fp8_f32(c, d, w, true); return (unsigned)w; }
; __device__ __forceinline__ void phase_ln1(const Args& a, LAS unsigned char* lds, const WCtx& w, int l, int nrows) {
;     ...
;         { unsigned* hrow = (unsigned*)((unsigned char*)H + (size_t)row * 1024);
; #pragma unroll
;           for (int j = 0; j < 4; ++j) { const f32x4 sh = *(const LAS f32x4*)(bv + 1024 + 4 * w.lane + 256 * j), sc = *(const LAS f32x4*)(bv + 2048 + 4 * w.lane + 256 * j);
;               hv[j] = (x[j] - mean) * rstd * (sc + 1.0f) + sh;
;               hrow[w.lane + 64 * j] = pk4_fp8(fminf(fmaxf(hv[j][0], -448.f), 448.f), fminf(fmaxf(hv[j][1], -448.f), 448.f), fminf(fmaxf(hv[j][2], -448.f), 448.f), fminf(fmaxf(hv[j][3], -448.f), 448.f)); } }
;         float pe[16];
; #pragma unroll
;         for (int e = 0; e < 16; ++e) { float p = 0.f;
; #pragma unroll
;             for (int j = 0; j < 4; ++j) { const f32x4 wv = (e < 10) ? wr[e < 10 ? e : 0][j] : *(const LAS f32x4*)(WRT + e * 1024 + 256 * j + 4 * w.lane); p += (hv[j][0] * wv[0] + hv[j][1] * wv[1]) + (hv[j][2] * wv[2] + hv[j][3] * wv[3]); }
;             pe[e] = p; }
;     ...
;         for (int k = 0; k < 8; ++k) q8[k] = swap32_add(pe[k], pe[k + 8]);
	v_pk_add_f32 v[194:195], v[222:223], 1.0 op_sel_hi:[1,0]
	v_pk_add_f32 v[220:221], v[220:221], 1.0 op_sel_hi:[1,0]
	v_pk_fma_f32 v[192:193], v[194:195], v[192:193], v[218:219]
	v_pk_fma_f32 v[194:195], v[220:221], v[224:225], v[216:217]
	v_mov_b32_e32 v220, v51
	v_med3_f32 v216, v194, s3, v236
	v_med3_f32 v217, v195, s3, v236
	v_cvt_pk_fp8_f32 v220, v216, v217
	v_med3_f32 v218, v192, s3, v236
	v_med3_f32 v219, v193, s3, v236
	v_lshl_add_u64 v[216:217], s[52:53], 0, v[204:205]
	v_cvt_pk_fp8_f32 v220, v218, v219 op_sel:[0,0,1]
	v_add_co_u32_e32 v216, vcc, s2, v216
	s_nop 1
	v_addc_co_u32_e32 v217, vcc, 0, v217, vcc
	global_store_dword v[216:217], v220, off
	ds_read_b128 v[218:221], v243 offset:5120
	ds_read_b128 v[222:225], v243 offset:9216
	s_waitcnt lgkmcnt(0)
	v_pk_add_f32 v[190:191], v[224:225], 1.0 op_sel_hi:[1,0]
	v_pk_add_f32 v[222:223], v[222:223], 1.0 op_sel_hi:[1,0]
	v_pk_fma_f32 v[188:189], v[190:191], v[188:189], v[220:221]
	v_pk_fma_f32 v[190:191], v[222:223], v[226:227], v[218:219]
	v_mov_b32_e32 v222, v51
	v_med3_f32 v218, v190, s3, v236
	v_med3_f32 v219, v191, s3, v236
	v_cvt_pk_fp8_f32 v222, v218, v219
	v_med3_f32 v220, v188, s3, v236
	v_med3_f32 v221, v189, s3, v236
	v_pk_mul_f32 v[226:227], v[184:185], v[50:51] op_sel_hi:[1,0]
	v_cvt_pk_fp8_f32 v222, v220, v221 op_sel:[0,0,1]
	v_pk_mul_f32 v[184:185], v[186:187], v[50:51] op_sel_hi:[1,0]
	global_store_dword v[216:217], v222, off offset:256
	ds_read_b128 v[218:221], v243 offset:6144
	ds_read_b128 v[222:225], v243 offset:10240
	s_waitcnt lgkmcnt(0)
	v_pk_add_f32 v[186:187], v[224:225], 1.0 op_sel_hi:[1,0]
	v_pk_add_f32 v[222:223], v[222:223], 1.0 op_sel_hi:[1,0]
	v_pk_fma_f32 v[184:185], v[184:185], v[186:187], v[220:221]
	v_pk_fma_f32 v[186:187], v[226:227], v[222:223], v[218:219]
	v_mov_b32_e32 v222, v51
	v_med3_f32 v218, v186, s3, v236
	v_med3_f32 v219, v187, s3, v236
	v_cvt_pk_fp8_f32 v222, v218, v219
	v_med3_f32 v220, v184, s3, v236
	v_med3_f32 v221, v185, s3, v236
	v_pk_mul_f32 v[226:227], v[180:181], v[50:51] op_sel_hi:[1,0]
	v_cvt_pk_fp8_f32 v222, v220, v221 op_sel:[0,0,1]
	v_pk_mul_f32 v[180:181], v[182:183], v[50:51] op_sel_hi:[1,0]
	global_store_dword v[216:217], v222, off offset:512
	ds_read_b128 v[218:221], v243 offset:7168
	ds_read_b128 v[222:225], v243 offset:11264
	ds_read_b128 v[244:247], v197 offset:40960
	s_waitcnt lgkmcnt(1)
	v_pk_add_f32 v[182:183], v[224:225], 1.0 op_sel_hi:[1,0]
	v_pk_add_f32 v[222:223], v[222:223], 1.0 op_sel_hi:[1,0]
	v_pk_fma_f32 v[180:181], v[180:181], v[182:183], v[220:221]
	v_pk_fma_f32 v[182:183], v[226:227], v[222:223], v[218:219]
	v_mov_b32_e32 v221, v51
	v_med3_f32 v50, v182, s3, v236
	v_med3_f32 v218, v183, s3, v236
	v_cvt_pk_fp8_f32 v221, v50, v218
	v_med3_f32 v219, v180, s3, v236
	v_med3_f32 v220, v181, s3, v236
	v_cvt_pk_fp8_f32 v221, v219, v220 op_sel:[0,0,1]
	global_store_dword v[216:217], v221, off offset:768
	ds_read_b128 v[224:227], v197 offset:41984
	v_pk_mul_f32 v[238:239], v[160:161], v[194:195]
	v_pk_fma_f32 v[238:239], v[162:163], v[192:193], v[238:239]
	v_pk_fma_f32 v[238:239], v[156:157], v[190:191], v[238:239]
	v_pk_fma_f32 v[238:239], v[158:159], v[188:189], v[238:239]
	v_pk_fma_f32 v[238:239], v[152:153], v[186:187], v[238:239]
	v_pk_fma_f32 v[238:239], v[154:155], v[184:185], v[238:239]
	v_pk_fma_f32 v[238:239], v[148:149], v[182:183], v[238:239]
	v_pk_fma_f32 v[238:239], v[150:151], v[180:181], v[238:239]
	v_add_f32_e32 v50, v238, v239
	v_pk_mul_f32 v[238:239], v[30:31], v[194:195]
	v_pk_fma_f32 v[238:239], v[32:33], v[192:193], v[238:239]
	v_pk_fma_f32 v[238:239], v[26:27], v[190:191], v[238:239]
	v_pk_fma_f32 v[238:239], v[28:29], v[188:189], v[238:239]
	v_pk_fma_f32 v[238:239], v[22:23], v[186:187], v[238:239]
	v_pk_fma_f32 v[238:239], v[24:25], v[184:185], v[238:239]
	v_pk_fma_f32 v[238:239], v[18:19], v[182:183], v[238:239]
	v_pk_fma_f32 v[238:239], v[20:21], v[180:181], v[238:239]
	v_add_f32_e32 v223, v238, v239
	s_nop 1
	v_permlane32_swap_b32_e32 v50, v223
	v_add_f32_e32 v50, v50, v223
	v_pk_mul_f32 v[238:239], v[144:145], v[194:195]
	v_pk_fma_f32 v[238:239], v[146:147], v[192:193], v[238:239]
	v_pk_fma_f32 v[238:239], v[140:141], v[190:191], v[238:239]
	v_pk_fma_f32 v[238:239], v[142:143], v[188:189], v[238:239]
	v_pk_fma_f32 v[238:239], v[136:137], v[186:187], v[238:239]
	v_pk_fma_f32 v[238:239], v[138:139], v[184:185], v[238:239]
	v_pk_fma_f32 v[238:239], v[132:133], v[182:183], v[238:239]
	v_pk_fma_f32 v[238:239], v[134:135], v[180:181], v[238:239]
	v_add_f32_e32 v216, v238, v239
	v_pk_mul_f32 v[238:239], v[14:15], v[194:195]
	v_pk_fma_f32 v[238:239], v[16:17], v[192:193], v[238:239]
	v_pk_fma_f32 v[238:239], v[10:11], v[190:191], v[238:239]
	v_pk_fma_f32 v[238:239], v[12:13], v[188:189], v[238:239]
	v_pk_fma_f32 v[238:239], v[6:7], v[186:187], v[238:239]
	v_pk_fma_f32 v[238:239], v[8:9], v[184:185], v[238:239]
	v_pk_fma_f32 v[238:239], v[2:3], v[182:183], v[238:239]
	v_pk_fma_f32 v[238:239], v[4:5], v[180:181], v[238:239]
	v_add_f32_e32 v243, v238, v239
	s_nop 1
	v_permlane32_swap_b32_e32 v216, v243
	v_add_f32_e32 v216, v216, v243
	s_waitcnt lgkmcnt(1)
	v_pk_mul_f32 v[248:249], v[244:245], v[194:195]
	v_pk_fma_f32 v[248:249], v[246:247], v[192:193], v[248:249]
	ds_read_b128 v[244:247], v197 offset:43008
	v_pk_mul_f32 v[238:239], v[128:129], v[194:195]
	v_pk_fma_f32 v[238:239], v[130:131], v[192:193], v[238:239]
	s_waitcnt lgkmcnt(1)
	v_pk_fma_f32 v[248:249], v[224:225], v[190:191], v[248:249]
	v_pk_fma_f32 v[248:249], v[226:227], v[188:189], v[248:249]
	ds_read_b128 v[224:227], v197 offset:44032
	v_pk_fma_f32 v[238:239], v[124:125], v[190:191], v[238:239]
	v_pk_fma_f32 v[238:239], v[126:127], v[188:189], v[238:239]
	s_waitcnt lgkmcnt(1)
; #define LAS __attribute__((address_space(3)))
; __device__ __forceinline__ float swap32_add(float a, float b) { const auto r = __builtin_amdgcn_permlane32_swap(__float_as_uint(a), __float_as_uint(b), false, false); return __uint_as_float(r[0]) + __uint_as_float(r[1]); }
; __device__ __forceinline__ void phase_ln1(const Args& a, LAS unsigned char* lds, const WCtx& w, int l, int nrows) {
;     ...
;         for (int e = 0; e < 16; ++e) { float p = 0.f;
; #pragma unroll
;             for (int j = 0; j < 4; ++j) { const f32x4 wv = (e < 10) ? wr[e < 10 ? e : 0][j] : *(const LAS f32x4*)(WRT + e * 1024 + 256 * j + 4 * w.lane); p += (hv[j][0] * wv[0] + hv[j][1] * wv[1]) + (hv[j][2] * wv[2] + hv[j][3] * wv[3]); }
;             pe[e] = p; }
;         float q8[8], q4[4], q2[2];
; #pragma unroll
;         for (int k = 0; k < 8; ++k) q8[k] = swap32_add(pe[k], pe[k + 8]);
	v_pk_fma_f32 v[248:249], v[244:245], v[186:187], v[248:249]
	v_pk_fma_f32 v[248:249], v[246:247], v[184:185], v[248:249]
	ds_read_b128 v[244:247], v197 offset:45056
	v_pk_fma_f32 v[238:239], v[120:121], v[186:187], v[238:239]
	v_pk_fma_f32 v[238:239], v[122:123], v[184:185], v[238:239]
	s_waitcnt lgkmcnt(1)
	v_pk_fma_f32 v[248:249], v[224:225], v[182:183], v[248:249]
	v_pk_fma_f32 v[248:249], v[226:227], v[180:181], v[248:249]
	ds_read_b128 v[224:227], v197 offset:46080
	v_pk_fma_f32 v[238:239], v[116:117], v[182:183], v[238:239]
	v_pk_fma_f32 v[238:239], v[118:119], v[180:181], v[238:239]
	v_add_f32_e32 v217, v238, v239
	v_add_f32_e32 v223, v248, v249
	s_nop 1
	v_permlane32_swap_b32_e32 v217, v223
	v_add_f32_e32 v217, v217, v223
	s_waitcnt lgkmcnt(1)
	v_pk_mul_f32 v[248:249], v[244:245], v[194:195]
	v_pk_fma_f32 v[248:249], v[246:247], v[192:193], v[248:249]
	ds_read_b128 v[244:247], v197 offset:47104
	v_pk_mul_f32 v[238:239], v[112:113], v[194:195]
	v_pk_fma_f32 v[238:239], v[114:115], v[192:193], v[238:239]
	s_waitcnt lgkmcnt(1)
	v_pk_fma_f32 v[248:249], v[224:225], v[190:191], v[248:249]
	v_pk_fma_f32 v[248:249], v[226:227], v[188:189], v[248:249]
	ds_read_b128 v[224:227], v197 offset:48128
	v_pk_fma_f32 v[238:239], v[108:109], v[190:191], v[238:239]
	v_pk_fma_f32 v[238:239], v[110:111], v[188:189], v[238:239]
	s_waitcnt lgkmcnt(1)
	v_pk_fma_f32 v[248:249], v[244:245], v[186:187], v[248:249]
	v_pk_fma_f32 v[248:249], v[246:247], v[184:185], v[248:249]
	ds_read_b128 v[244:247], v197 offset:49152
	v_pk_fma_f32 v[238:239], v[104:105], v[186:187], v[238:239]
	v_pk_fma_f32 v[238:239], v[106:107], v[184:185], v[238:239]
	s_waitcnt lgkmcnt(1)
	v_pk_fma_f32 v[248:249], v[224:225], v[182:183], v[248:249]
	v_pk_fma_f32 v[248:249], v[226:227], v[180:181], v[248:249]
	ds_read_b128 v[224:227], v197 offset:50176
	v_pk_fma_f32 v[238:239], v[100:101], v[182:183], v[238:239]
	v_pk_fma_f32 v[238:239], v[102:103], v[180:181], v[238:239]
	v_add_f32_e32 v218, v238, v239
	v_add_f32_e32 v223, v248, v249
	s_nop 1
	v_permlane32_swap_b32_e32 v218, v223
	v_add_f32_e32 v218, v218, v223
	s_waitcnt lgkmcnt(1)
	v_pk_mul_f32 v[248:249], v[244:245], v[194:195]
	v_pk_fma_f32 v[248:249], v[246:247], v[192:193], v[248:249]
	ds_read_b128 v[244:247], v197 offset:51200
	v_pk_mul_f32 v[238:239], v[96:97], v[194:195]
	v_pk_fma_f32 v[238:239], v[98:99], v[192:193], v[238:239]
	s_waitcnt lgkmcnt(1)
	v_pk_fma_f32 v[248:249], v[224:225], v[190:191], v[248:249]
	v_pk_fma_f32 v[248:249], v[226:227], v[188:189], v[248:249]
	ds_read_b128 v[224:227], v197 offset:52224
	v_pk_fma_f32 v[238:239], v[92:93], v[190:191], v[238:239]
	v_pk_fma_f32 v[238:239], v[94:95], v[188:189], v[238:239]
	s_waitcnt lgkmcnt(1)
	v_pk_fma_f32 v[248:249], v[244:245], v[186:187], v[248:249]
	v_pk_fma_f32 v[248:249], v[246:247], v[184:185], v[248:249]
	ds_read_b128 v[244:247], v197 offset:53248
	v_pk_fma_f32 v[238:239], v[88:89], v[186:187], v[238:239]
	v_pk_fma_f32 v[238:239], v[90:91], v[184:185], v[238:239]
	s_waitcnt lgkmcnt(1)
	v_pk_fma_f32 v[248:249], v[224:225], v[182:183], v[248:249]
	v_pk_fma_f32 v[248:249], v[226:227], v[180:181], v[248:249]
	ds_read_b128 v[224:227], v197 offset:54272
	v_pk_fma_f32 v[238:239], v[84:85], v[182:183], v[238:239]
	v_pk_fma_f32 v[238:239], v[86:87], v[180:181], v[238:239]
	v_add_f32_e32 v219, v238, v239
	v_add_f32_e32 v223, v248, v249
	s_nop 1
	v_permlane32_swap_b32_e32 v219, v223
	v_add_f32_e32 v219, v219, v223
	s_waitcnt lgkmcnt(1)
	v_pk_mul_f32 v[248:249], v[244:245], v[194:195]
	v_pk_fma_f32 v[248:249], v[246:247], v[192:193], v[248:249]
	ds_read_b128 v[244:247], v197 offset:55296
	v_pk_mul_f32 v[238:239], v[80:81], v[194:195]
	v_pk_fma_f32 v[238:239], v[82:83], v[192:193], v[238:239]
	s_waitcnt lgkmcnt(1)
	v_pk_fma_f32 v[248:249], v[224:225], v[190:191], v[248:249]
	v_pk_fma_f32 v[248:249], v[226:227], v[188:189], v[248:249]
	ds_read_b128 v[224:227], v197 offset:56320
	v_pk_fma_f32 v[238:239], v[76:77], v[190:191], v[238:239]
	v_pk_fma_f32 v[238:239], v[78:79], v[188:189], v[238:239]
	s_waitcnt lgkmcnt(1)
	v_pk_fma_f32 v[248:249], v[244:245], v[186:187], v[248:249]
	v_pk_fma_f32 v[248:249], v[246:247], v[184:185], v[248:249]
	ds_read_b128 v[244:247], v197 offset:57344
	v_pk_fma_f32 v[238:239], v[72:73], v[186:187], v[238:239]
	v_pk_fma_f32 v[238:239], v[74:75], v[184:185], v[238:239]
	s_waitcnt lgkmcnt(1)
	v_pk_fma_f32 v[248:249], v[224:225], v[182:183], v[248:249]
	v_pk_fma_f32 v[248:249], v[226:227], v[180:181], v[248:249]
	ds_read_b128 v[224:227], v197 offset:58368
	v_pk_fma_f32 v[238:239], v[68:69], v[182:183], v[238:239]
	v_pk_fma_f32 v[238:239], v[70:71], v[180:181], v[238:239]
	v_add_f32_e32 v220, v238, v239
	v_add_f32_e32 v223, v248, v249
	s_nop 1
	v_permlane32_swap_b32_e32 v220, v223
	v_add_f32_e32 v220, v220, v223
	s_waitcnt lgkmcnt(1)
	v_pk_mul_f32 v[248:249], v[244:245], v[194:195]
	v_pk_fma_f32 v[248:249], v[246:247], v[192:193], v[248:249]
	ds_read_b128 v[244:247], v197 offset:59392
	v_pk_mul_f32 v[238:239], v[64:65], v[194:195]
	v_pk_fma_f32 v[238:239], v[66:67], v[192:193], v[238:239]
	s_waitcnt lgkmcnt(1)
	v_pk_fma_f32 v[248:249], v[224:225], v[190:191], v[248:249]
	v_pk_fma_f32 v[248:249], v[226:227], v[188:189], v[248:249]
	ds_read_b128 v[224:227], v197 offset:60416
	v_pk_fma_f32 v[238:239], v[60:61], v[190:191], v[238:239]
	v_pk_fma_f32 v[238:239], v[62:63], v[188:189], v[238:239]
	s_waitcnt lgkmcnt(1)
; __device__ __forceinline__ float dpp_x4(float x) { return dpp_x3(dpp_x7(x)); }
; __device__ __forceinline__ float dpp_x8(float x) { return __int_as_float(__builtin_amdgcn_mov_dpp(__float_as_int(x), 0x128, 0xf, 0xf, true)); }
; __device__ __forceinline__ float swap16_add(float a, float b) { const auto r = __builtin_amdgcn_permlane16_swap(__float_as_uint(a), __float_as_uint(b), false, false); return __uint_as_float(r[0]) + __uint_as_float(r[1]); }
; __device__ __forceinline__ float swap32_add(float a, float b) { const auto r = __builtin_amdgcn_permlane32_swap(__float_as_uint(a), __float_as_uint(b), false, false); return __uint_as_float(r[0]) + __uint_as_float(r[1]); }
; __device__ __forceinline__ float swap16_max(float a) { const auto r = __builtin_amdgcn_permlane16_swap(__float_as_uint(a), __float_as_uint(a), false, false); return fmaxf(__uint_as_float(r[0]), __uint_as_float(r[1])); }
; __device__ __forceinline__ float swap32_max(float a) { const auto r = __builtin_amdgcn_permlane32_swap(__float_as_uint(a), __float_as_uint(a), false, false); return fmaxf(__uint_as_float(r[0]), __uint_as_float(r[1])); }
; __device__ __forceinline__ float dpp_xor1(float x) { return __int_as_float(__builtin_amdgcn_mov_dpp(__float_as_int(x), 0xB1, 0xf, 0xf, true)); }
; __device__ __forceinline__ void phase_ln1(const Args& a, LAS unsigned char* lds, const WCtx& w, int l, int nrows) {
;     ...
;         for (int k = 0; k < 8; ++k) q8[k] = swap32_add(pe[k], pe[k + 8]);
; #pragma unroll
;         for (int k = 0; k < 4; ++k) q4[k] = swap16_add(q8[k], q8[k + 4]);
;         { const bool hi = (w.lane & 8) != 0;
; #pragma unroll
;           for (int k = 0; k < 2; ++k) { const float mine = hi ? q4[k + 2] : q4[k], oth = hi ? q4[k] : q4[k + 2]; q2[k] = mine + dpp_x8(oth); } }
;         float lg;
;         { const bool hi = (w.lane & 4) != 0; const float mine = hi ? q2[1] : q2[0], oth = hi ? q2[0] : q2[1]; lg = mine + dpp_x4(oth); }
;         lg += dpp_xor1(lg); lg += dpp_xor2(lg);
;         float mx = lg;
;         mx = fmaxf(mx, dpp_x4(mx)); mx = fmaxf(mx, dpp_x8(mx)); mx = swap16_max(mx); mx = swap32_max(mx);
;         const float ex = __expf(lg - mx); float s = ex;
;         s += dpp_x4(s); s += dpp_x8(s); s = swap16_add(s, s); s = swap32_add(s, s);
;         if ((w.lane & 3) == 0) AFF[(size_t)row * 16 + (w.lane >> 2)] = ex / s;
	v_pk_fma_f32 v[248:249], v[244:245], v[186:187], v[248:249]
	v_pk_fma_f32 v[248:249], v[246:247], v[184:185], v[248:249]
	ds_read_b128 v[244:247], v197 offset:61440
	v_pk_fma_f32 v[238:239], v[56:57], v[186:187], v[238:239]
	v_pk_fma_f32 v[238:239], v[58:59], v[184:185], v[238:239]
	s_waitcnt lgkmcnt(1)
	v_pk_fma_f32 v[248:249], v[224:225], v[182:183], v[248:249]
	v_pk_fma_f32 v[248:249], v[226:227], v[180:181], v[248:249]
	ds_read_b128 v[224:227], v197 offset:62464
	v_pk_fma_f32 v[238:239], v[52:53], v[182:183], v[238:239]
	v_pk_fma_f32 v[238:239], v[54:55], v[180:181], v[238:239]
	v_add_f32_e32 v221, v238, v239
	v_add_f32_e32 v223, v248, v249
	s_nop 1
	v_permlane32_swap_b32_e32 v221, v223
	v_add_f32_e32 v221, v221, v223
	s_waitcnt lgkmcnt(1)
	v_pk_mul_f32 v[248:249], v[244:245], v[194:195]
	v_pk_fma_f32 v[248:249], v[246:247], v[192:193], v[248:249]
	ds_read_b128 v[244:247], v197 offset:63488
	v_pk_mul_f32 v[238:239], v[46:47], v[194:195]
	v_pk_fma_f32 v[238:239], v[48:49], v[192:193], v[238:239]
	s_waitcnt lgkmcnt(1)
	v_pk_fma_f32 v[248:249], v[224:225], v[190:191], v[248:249]
	v_pk_fma_f32 v[248:249], v[226:227], v[188:189], v[248:249]
	ds_read_b128 v[224:227], v197 offset:64512
	v_pk_fma_f32 v[238:239], v[42:43], v[190:191], v[238:239]
	v_pk_fma_f32 v[238:239], v[44:45], v[188:189], v[238:239]
	s_waitcnt lgkmcnt(1)
	v_pk_fma_f32 v[248:249], v[244:245], v[186:187], v[248:249]
	v_pk_fma_f32 v[248:249], v[246:247], v[184:185], v[248:249]
	v_pk_fma_f32 v[238:239], v[38:39], v[186:187], v[238:239]
	v_pk_fma_f32 v[238:239], v[40:41], v[184:185], v[238:239]
	s_waitcnt lgkmcnt(0)
	v_pk_fma_f32 v[248:249], v[224:225], v[182:183], v[248:249]
	v_pk_fma_f32 v[248:249], v[226:227], v[180:181], v[248:249]
	v_pk_fma_f32 v[238:239], v[34:35], v[182:183], v[238:239]
	v_pk_fma_f32 v[238:239], v[36:37], v[180:181], v[238:239]
	v_add_f32_e32 v222, v238, v239
	v_add_f32_e32 v223, v248, v249
	s_nop 1
	v_permlane32_swap_b32_e32 v222, v223
	v_add_f32_e32 v222, v222, v223
	v_mov_b32_e32 v181, v216
	v_mov_b32_e32 v182, v217
	v_mov_b32_e32 v183, v218
	v_mov_b32_e32 v184, v219
	v_mov_b32_e32 v185, v220
	v_mov_b32_e32 v186, v221
	v_mov_b32_e32 v180, v222
	v_permlane16_swap_b32_e32 v50, v184
	v_permlane16_swap_b32_e32 v181, v185
	v_permlane16_swap_b32_e32 v182, v186
	v_permlane16_swap_b32_e32 v183, v180
	v_add_f32_e32 v50, v50, v184
	v_add_f32_e32 v181, v181, v185
	v_add_f32_e32 v182, v182, v186
	v_add_f32_e32 v180, v183, v180
	v_cndmask_b32_e64 v183, v182, v50, s[0:1]
	v_cndmask_b32_e64 v50, v50, v182, s[0:1]
	v_cndmask_b32_e64 v182, v180, v181, s[0:1]
	v_cndmask_b32_e64 v180, v181, v180, s[0:1]
	v_add_f32_dpp v50, v50, v183 row_ror:8 row_mask:0xf bank_mask:0xf bound_ctrl:1
	s_nop 0
	v_add_f32_dpp v180, v180, v182 row_ror:8 row_mask:0xf bank_mask:0xf bound_ctrl:1
	v_cndmask_b32_e64 v181, v180, v50, s[36:37]
	v_cndmask_b32_e64 v50, v50, v180, s[36:37]
	s_nop 1
	v_mov_b32_dpp v50, v50 row_half_mirror row_mask:0xf bank_mask:0xf bound_ctrl:1
	s_nop 1
	v_add_f32_dpp v50, v50, v181 quad_perm:[3,2,1,0] row_mask:0xf bank_mask:0xf bound_ctrl:1
	s_nop 1
	v_add_f32_dpp v50, v50, v50 quad_perm:[1,0,3,2] row_mask:0xf bank_mask:0xf bound_ctrl:1
	s_nop 1
	v_add_f32_dpp v50, v50, v50 quad_perm:[2,3,0,1] row_mask:0xf bank_mask:0xf bound_ctrl:1
	s_nop 1
	v_mov_b32_dpp v180, v50 row_half_mirror row_mask:0xf bank_mask:0xf bound_ctrl:1
	s_nop 1
	v_mov_b32_dpp v180, v180 quad_perm:[3,2,1,0] row_mask:0xf bank_mask:0xf bound_ctrl:1
	v_max_f32_e32 v180, v180, v180
	v_max_f32_e32 v180, v50, v180
	s_nop 1
	v_mov_b32_dpp v181, v180 row_ror:8 row_mask:0xf bank_mask:0xf bound_ctrl:1
	v_max_f32_e32 v181, v181, v181
	v_max_f32_e32 v180, v180, v181
	v_mov_b32_e32 v181, v180
	s_nop 1
	v_permlane16_swap_b32_e32 v180, v181
	v_max_f32_e32 v181, v181, v181
	v_max_f32_e32 v180, v180, v180
	v_max_f32_e32 v180, v180, v181
	v_mov_b32_e32 v181, v180
	s_nop 1
	v_permlane32_swap_b32_e32 v180, v181
	v_max_f32_e32 v181, v181, v181
	v_max_f32_e32 v180, v180, v180
	v_max_f32_e32 v180, v180, v181
	v_sub_f32_e32 v50, v50, v180
	v_mul_f32_e32 v50, 0x3fb8aa3b, v50
	v_exp_f32_e32 v50, v50
	s_nop 1
	v_mov_b32_dpp v180, v50 row_half_mirror row_mask:0xf bank_mask:0xf bound_ctrl:1
	s_nop 1
	v_add_f32_dpp v180, v180, v50 quad_perm:[3,2,1,0] row_mask:0xf bank_mask:0xf bound_ctrl:1
	s_nop 1
	v_add_f32_dpp v180, v180, v180 row_ror:8 row_mask:0xf bank_mask:0xf bound_ctrl:1
	v_mov_b32_e32 v181, v180
	s_nop 1
	v_permlane16_swap_b32_e32 v180, v181
	v_add_f32_e32 v180, v180, v181
	v_mov_b32_e32 v181, v180
	s_nop 1
	v_permlane32_swap_b32_e32 v180, v181
	s_and_saveexec_b64 s[2:3], s[40:41]
	s_cbranch_execz .LBB0_2162
	v_add_f32_e32 v180, v180, v181
	v_div_scale_f32 v181, s[4:5], v180, v180, v50
	v_rcp_f32_e32 v182, v181
	v_div_scale_f32 v183, vcc, v50, v180, v50
	v_fma_f32 v184, -v181, v182, 1.0
	v_fmac_f32_e32 v182, v184, v182
	v_mul_f32_e32 v184, v183, v182
	v_fma_f32 v185, -v181, v184, v183
	v_fmac_f32_e32 v184, v185, v182
	v_fma_f32 v181, -v181, v184, v183
	v_div_fmas_f32 v181, v181, v182, v184
	v_div_fixup_f32 v50, v181, v180, v50
	v_lshl_add_u64 v[180:181], s[52:53], 0, v[200:201]
	global_store_dword v[180:181], v50, off
	s_branch .LBB0_2162
